# counted waits: attention main-loop step barriers keep the 4 next-QK K-fragment reads in flight (lgkmcnt(4) instead of 0)
# baseline (speedup 1.0000x reference)
.LBB0_833:
	s_waitcnt lgkmcnt(6)
	v_mfma_f32_32x32x16_bf16 v[48:63], v[180:183], v[6:9], v[48:63]
	v_exp_f32_e32 v128, v128
	v_exp_f32_e32 v129, v129
	v_exp_f32_e32 v130, v130
	v_exp_f32_e32 v131, v131
	ds_read_b64_tr_b16 v[6:7], v14 offset:51200
	ds_read_b64_tr_b16 v[8:9], v14 offset:51712
	s_waitcnt lgkmcnt(6)
	v_mfma_f32_32x32x16_bf16 v[32:47], v[180:183], v[10:13], v[32:47]
	v_exp_f32_e32 v132, v132
	v_exp_f32_e32 v133, v133
	v_exp_f32_e32 v134, v134
	v_exp_f32_e32 v135, v135
	ds_read_b64_tr_b16 v[10:11], v14 offset:55296
	ds_read_b64_tr_b16 v[12:13], v14 offset:55808
	s_waitcnt lgkmcnt(6)
	v_mfma_f32_32x32x16_bf16 v[48:63], v[172:175], v[80:83], v[48:63]
	v_exp_f32_e32 v136, v136
	v_exp_f32_e32 v137, v137
	v_exp_f32_e32 v138, v138
	v_exp_f32_e32 v139, v139
	ds_read_b64_tr_b16 v[80:81], v14 offset:52224
	ds_read_b64_tr_b16 v[82:83], v14 offset:52736
	s_waitcnt lgkmcnt(6)
	v_mfma_f32_32x32x16_bf16 v[32:47], v[172:175], v[2:5], v[32:47]
	v_exp_f32_e32 v140, v140
	v_exp_f32_e32 v141, v141
	v_exp_f32_e32 v142, v142
	v_exp_f32_e32 v143, v143
	v_add_u32_e32 v15, s12, v214
	ds_read_b64_tr_b16 v[84:85], v14 offset:56320
	ds_read_b64_tr_b16 v[86:87], v14 offset:56832
	ds_read_b128 v[2:5], v15
	s_waitcnt lgkmcnt(7)
	v_mfma_f32_32x32x16_bf16 v[48:63], v[160:163], v[6:9], v[48:63]
	v_exp_f32_e32 v112, v112
	v_exp_f32_e32 v113, v113
	v_exp_f32_e32 v114, v114
	v_exp_f32_e32 v115, v115
	ds_read_b128 v[6:9], v15 offset:512
	s_waitcnt lgkmcnt(6)
	v_mfma_f32_32x32x16_bf16 v[32:47], v[160:163], v[10:13], v[32:47]
	v_exp_f32_e32 v116, v116
	v_exp_f32_e32 v117, v117
	v_exp_f32_e32 v118, v118
	v_exp_f32_e32 v119, v119
	ds_read_b128 v[10:13], v15 offset:2048
	s_waitcnt lgkmcnt(5)
	v_mfma_f32_32x32x16_bf16 v[48:63], v[152:155], v[80:83], v[48:63]
	v_exp_f32_e32 v120, v120
	v_exp_f32_e32 v121, v121
	v_exp_f32_e32 v122, v122
	v_exp_f32_e32 v123, v123
	ds_read_b128 v[184:187], v15 offset:2560
	s_waitcnt lgkmcnt(4)
	v_mfma_f32_32x32x16_bf16 v[32:47], v[152:155], v[84:87], v[32:47]
	v_exp_f32_e32 v124, v124
	v_exp_f32_e32 v125, v125
	v_exp_f32_e32 v126, v126
	v_exp_f32_e32 v127, v127
	s_add_i32 s12, s23, 0x2000
	s_cmpk_lg_i32 s23, 0x4000
	s_cselect_b32 s12, s12, 0
	s_waitcnt vmcnt(3) lgkmcnt(4)
	s_barrier
	s_andn2_b64 vcc, exec, s[62:63]
	s_cbranch_vccz .Latt_rA

.LBB0_836:
	s_waitcnt lgkmcnt(6)
	v_mfma_f32_32x32x16_bf16 v[48:63], v[180:183], v[112:115], v[48:63]
	v_exp_f32_e32 v96, v96
	v_exp_f32_e32 v97, v97
	v_exp_f32_e32 v98, v98
	v_exp_f32_e32 v99, v99
	ds_read_b64_tr_b16 v[112:113], v14 offset:51200
	ds_read_b64_tr_b16 v[114:115], v14 offset:51712
	s_waitcnt lgkmcnt(6)
	v_mfma_f32_32x32x16_bf16 v[32:47], v[180:183], v[10:13], v[32:47]
	v_exp_f32_e32 v100, v100
	v_exp_f32_e32 v101, v101
	v_exp_f32_e32 v102, v102
	v_exp_f32_e32 v103, v103
	ds_read_b64_tr_b16 v[10:11], v14 offset:55296
	ds_read_b64_tr_b16 v[12:13], v14 offset:55808
	s_waitcnt lgkmcnt(6)
	v_mfma_f32_32x32x16_bf16 v[48:63], v[172:175], v[6:9], v[48:63]
	v_exp_f32_e32 v104, v104
	v_exp_f32_e32 v105, v105
	v_exp_f32_e32 v106, v106
	v_exp_f32_e32 v107, v107
	ds_read_b64_tr_b16 v[6:7], v14 offset:52224
	ds_read_b64_tr_b16 v[8:9], v14 offset:52736
	s_waitcnt lgkmcnt(6)
	v_mfma_f32_32x32x16_bf16 v[32:47], v[172:175], v[2:5], v[32:47]
	v_exp_f32_e32 v108, v108
	v_exp_f32_e32 v109, v109
	v_exp_f32_e32 v110, v110
	v_exp_f32_e32 v111, v111
	v_add_u32_e32 v0, s22, v214
	ds_read_b64_tr_b16 v[2:3], v14 offset:56320
	ds_read_b64_tr_b16 v[4:5], v14 offset:56832
	ds_read_b128 v[196:199], v0
	s_waitcnt lgkmcnt(7)
	v_mfma_f32_32x32x16_bf16 v[48:63], v[160:163], v[112:115], v[48:63]
	v_exp_f32_e32 v80, v80
	v_exp_f32_e32 v81, v81
	v_exp_f32_e32 v82, v82
	v_exp_f32_e32 v83, v83
	ds_read_b128 v[184:187], v0 offset:512
	s_waitcnt lgkmcnt(6)
	v_mfma_f32_32x32x16_bf16 v[32:47], v[160:163], v[10:13], v[32:47]
	v_exp_f32_e32 v84, v84
	v_exp_f32_e32 v85, v85
	v_exp_f32_e32 v86, v86
	v_exp_f32_e32 v87, v87
	ds_read_b128 v[188:191], v0 offset:2048
	s_waitcnt lgkmcnt(5)
	v_mfma_f32_32x32x16_bf16 v[48:63], v[152:155], v[6:9], v[48:63]
	v_exp_f32_e32 v88, v88
	v_exp_f32_e32 v89, v89
	v_exp_f32_e32 v90, v90
	v_exp_f32_e32 v91, v91
	ds_read_b128 v[192:195], v0 offset:2560
	s_waitcnt lgkmcnt(4)
	v_mfma_f32_32x32x16_bf16 v[32:47], v[152:155], v[2:5], v[32:47]
	v_exp_f32_e32 v92, v92
	v_exp_f32_e32 v93, v93
	v_exp_f32_e32 v94, v94
	v_exp_f32_e32 v95, v95
	s_add_i32 s22, s12, 0x2000
	s_cmpk_lg_i32 s12, 0x4000
	s_cselect_b32 s22, s22, 0
	s_add_u32 s60, s60, 0x2000
	s_addc_u32 s61, s61, 0
	s_add_u32 s58, s58, 0x20000
	s_addc_u32 s59, s59, 0
	s_add_i32 s67, s67, 2
	s_add_u32 s6, s6, 0x20000
	s_addc_u32 s7, s7, 0
	s_cmp_ge_i32 s10, s66
	s_cbranch_scc1 .Latt_mx
	s_mov_b32 s101, s23
	s_mov_b32 s10, s12
	s_mov_b32 s23, s22
	s_waitcnt vmcnt(3) lgkmcnt(4)
	s_barrier
	s_andn2_b64 vcc, exec, s[62:63]
	s_cbranch_vccnz .LBB0_832
	s_waitcnt lgkmcnt(0)
	ds_read_b128 v[2:5], v207 offset:96
	ds_read_b128 v[6:9], v207 offset:64
	ds_read_b128 v[10:13], v207 offset:32
	ds_read_b128 v[112:115], v207
	s_waitcnt lgkmcnt(3)
	v_pk_mul_f32 v[62:63], v[62:63], v[4:5]
	s_waitcnt lgkmcnt(2)
	v_pk_mul_f32 v[58:59], v[58:59], v[8:9]
	s_waitcnt lgkmcnt(1)
	v_pk_mul_f32 v[54:55], v[54:55], v[12:13]
	s_waitcnt lgkmcnt(0)
	v_pk_mul_f32 v[50:51], v[50:51], v[114:115]
	v_pk_mul_f32 v[60:61], v[60:61], v[2:3]
	v_pk_mul_f32 v[56:57], v[56:57], v[6:7]
	v_pk_mul_f32 v[52:53], v[52:53], v[10:11]
	v_pk_mul_f32 v[48:49], v[48:49], v[112:113]
	v_pk_mul_f32 v[46:47], v[46:47], v[4:5]
	v_pk_mul_f32 v[42:43], v[42:43], v[8:9]
	v_pk_mul_f32 v[38:39], v[38:39], v[12:13]
	v_pk_mul_f32 v[34:35], v[34:35], v[114:115]
	v_pk_mul_f32 v[44:45], v[44:45], v[2:3]
	v_pk_mul_f32 v[40:41], v[40:41], v[6:7]
	v_pk_mul_f32 v[36:37], v[36:37], v[10:11]
	v_pk_mul_f32 v[32:33], v[32:33], v[112:113]
	s_branch .LBB0_832
